# flattened-barrier version + epilogue-head pads trimmed to 8 states + no s_sleep between grid-barrier polls
# baseline (speedup 1.0000x reference)
.LBB0_114:
	global_load_dword v15, v16, s[10:11] sc1
	global_load_dword v0, v16, s[12:13] sc1
	global_load_dword v1, v16, s[14:15] sc1
	global_load_dword v2, v16, s[16:17] sc1
	global_load_dword v3, v16, s[18:19] sc1
	global_load_dword v4, v16, s[20:21] sc1
	global_load_dword v5, v16, s[22:23] sc1
	global_load_dword v6, v16, s[24:25] sc1
	global_load_dword v7, v16, s[26:27] sc1
	global_load_dword v8, v16, s[30:31] sc1
	global_load_dword v9, v16, s[34:35] sc1
	global_load_dword v10, v16, s[36:37] sc1
	global_load_dword v11, v16, s[38:39] sc1
	global_load_dword v12, v16, s[40:41] sc1
	global_load_dword v13, v16, s[42:43] sc1
	global_load_dword v14, v16, s[44:45] sc1
	s_mov_b64 s[46:47], -1
	s_mov_b64 s[48:49], -1
	s_waitcnt vmcnt(14)
	v_add_u32_e32 v17, v0, v15
	s_waitcnt vmcnt(13)
	v_add_u32_e32 v17, v17, v1
	s_waitcnt vmcnt(12)
	v_add_u32_e32 v17, v17, v2
	s_waitcnt vmcnt(11)
	v_add_u32_e32 v17, v17, v3
	s_waitcnt vmcnt(10)
	v_add_u32_e32 v17, v17, v4
	s_waitcnt vmcnt(9)
	v_add_u32_e32 v17, v17, v5
	s_waitcnt vmcnt(8)
	v_add_u32_e32 v17, v17, v6
	s_waitcnt vmcnt(7)
	v_add_u32_e32 v17, v17, v7
	s_waitcnt vmcnt(6)
	v_add_u32_e32 v17, v17, v8
	s_waitcnt vmcnt(5)
	v_add_u32_e32 v17, v17, v9
	s_waitcnt vmcnt(4)
	v_add_u32_e32 v17, v17, v10
	s_waitcnt vmcnt(3)
	v_add_u32_e32 v17, v17, v11
	s_waitcnt vmcnt(2)
	v_add_u32_e32 v17, v17, v12
	s_waitcnt vmcnt(1)
	v_add_u32_e32 v17, v17, v13
	s_waitcnt vmcnt(0)
	v_add_u32_e32 v17, v17, v14
	v_cmp_eq_u32_e32 vcc, s1, v17
	s_cbranch_vccnz .LBB0_113
	s_and_b32 s28, s3, 0xff
	s_cmp_eq_u32 s28, 0
	s_mov_b64 s[50:51], -1
	s_cbranch_scc1 .LBB0_118
	s_and_b64 vcc, exec, s[50:51]
	s_cbranch_vccz .LBB0_113

.LBB0_132:
	s_and_b32 s1, s0, 0xff
	s_mov_b64 s[22:23], -1
	s_cmp_lg_u32 s1, 0
	s_mov_b64 s[26:27], -1
	s_cbranch_scc0 .LBB0_135
	s_and_b64 vcc, exec, s[26:27]
	s_cbranch_vccz .LBB0_131

.LBB0_149:
	s_and_b32 s1, s0, 0xff
	s_cmp_lg_u32 s1, 0
	s_mov_b64 s[24:25], -1
	s_cbranch_scc0 .LBB0_152
	s_mov_b64 s[26:27], -1
	s_and_b64 vcc, exec, s[24:25]
	s_cbranch_vccz .LBB0_148

.LBB0_330:
	global_load_dword v15, v16, s[10:11] sc1
	global_load_dword v0, v16, s[12:13] sc1
	global_load_dword v1, v16, s[14:15] sc1
	global_load_dword v2, v16, s[16:17] sc1
	global_load_dword v3, v16, s[18:19] sc1
	global_load_dword v4, v16, s[22:23] sc1
	global_load_dword v5, v16, s[24:25] sc1
	global_load_dword v6, v16, s[26:27] sc1
	global_load_dword v7, v16, s[34:35] sc1
	global_load_dword v8, v16, s[36:37] sc1
	global_load_dword v9, v16, s[38:39] sc1
	global_load_dword v10, v16, s[40:41] sc1
	global_load_dword v11, v16, s[42:43] sc1
	global_load_dword v12, v16, s[44:45] sc1
	global_load_dword v13, v16, s[46:47] sc1
	global_load_dword v14, v16, s[48:49] sc1
	s_mov_b64 s[50:51], -1
	s_mov_b64 s[52:53], -1
	s_waitcnt vmcnt(14)
	v_add_u32_e32 v17, v0, v15
	s_waitcnt vmcnt(13)
	v_add_u32_e32 v17, v17, v1
	s_waitcnt vmcnt(12)
	v_add_u32_e32 v17, v17, v2
	s_waitcnt vmcnt(11)
	v_add_u32_e32 v17, v17, v3
	s_waitcnt vmcnt(10)
	v_add_u32_e32 v17, v17, v4
	s_waitcnt vmcnt(9)
	v_add_u32_e32 v17, v17, v5
	s_waitcnt vmcnt(8)
	v_add_u32_e32 v17, v17, v6
	s_waitcnt vmcnt(7)
	v_add_u32_e32 v17, v17, v7
	s_waitcnt vmcnt(6)
	v_add_u32_e32 v17, v17, v8
	s_waitcnt vmcnt(5)
	v_add_u32_e32 v17, v17, v9
	s_waitcnt vmcnt(4)
	v_add_u32_e32 v17, v17, v10
	s_waitcnt vmcnt(3)
	v_add_u32_e32 v17, v17, v11
	s_waitcnt vmcnt(2)
	v_add_u32_e32 v17, v17, v12
	s_waitcnt vmcnt(1)
	v_add_u32_e32 v17, v17, v13
	s_waitcnt vmcnt(0)
	v_add_u32_e32 v17, v17, v14
	v_cmp_eq_u32_e32 vcc, s1, v17
	s_cbranch_vccnz .LBB0_329
	s_and_b32 s28, s3, 0xff
	s_cmp_eq_u32 s28, 0
	s_mov_b64 s[54:55], -1
	s_cbranch_scc1 .LBB0_334
	s_and_b64 vcc, exec, s[54:55]
	s_cbranch_vccz .LBB0_329

.LBB0_348:
	s_and_b32 s1, s0, 0xff
	s_mov_b64 s[24:25], -1
	s_cmp_lg_u32 s1, 0
	s_mov_b64 s[34:35], -1
	s_cbranch_scc0 .LBB0_351
	s_and_b64 vcc, exec, s[34:35]
	s_cbranch_vccz .LBB0_347

.LBB0_365:
	s_and_b32 s1, s0, 0xff
	s_cmp_lg_u32 s1, 0
	s_mov_b64 s[26:27], -1
	s_cbranch_scc0 .LBB0_368
	s_mov_b64 s[34:35], -1
	s_and_b64 vcc, exec, s[26:27]
	s_cbranch_vccz .LBB0_364

.LBB0_570:
	global_load_dword v15, v16, s[10:11] sc1
	global_load_dword v0, v16, s[12:13] sc1
	global_load_dword v1, v16, s[14:15] sc1
	global_load_dword v2, v16, s[16:17] sc1
	global_load_dword v3, v16, s[18:19] sc1
	global_load_dword v4, v16, s[20:21] sc1
	global_load_dword v5, v16, s[22:23] sc1
	global_load_dword v6, v16, s[24:25] sc1
	global_load_dword v7, v16, s[34:35] sc1
	global_load_dword v8, v16, s[36:37] sc1
	global_load_dword v9, v16, s[38:39] sc1
	global_load_dword v10, v16, s[40:41] sc1
	global_load_dword v11, v16, s[42:43] sc1
	global_load_dword v12, v16, s[44:45] sc1
	global_load_dword v13, v16, s[46:47] sc1
	global_load_dword v14, v16, s[48:49] sc1
	s_mov_b64 s[50:51], -1
	s_mov_b64 s[52:53], -1
	s_waitcnt vmcnt(14)
	v_add_u32_e32 v17, v0, v15
	s_waitcnt vmcnt(13)
	v_add_u32_e32 v17, v17, v1
	s_waitcnt vmcnt(12)
	v_add_u32_e32 v17, v17, v2
	s_waitcnt vmcnt(11)
	v_add_u32_e32 v17, v17, v3
	s_waitcnt vmcnt(10)
	v_add_u32_e32 v17, v17, v4
	s_waitcnt vmcnt(9)
	v_add_u32_e32 v17, v17, v5
	s_waitcnt vmcnt(8)
	v_add_u32_e32 v17, v17, v6
	s_waitcnt vmcnt(7)
	v_add_u32_e32 v17, v17, v7
	s_waitcnt vmcnt(6)
	v_add_u32_e32 v17, v17, v8
	s_waitcnt vmcnt(5)
	v_add_u32_e32 v17, v17, v9
	s_waitcnt vmcnt(4)
	v_add_u32_e32 v17, v17, v10
	s_waitcnt vmcnt(3)
	v_add_u32_e32 v17, v17, v11
	s_waitcnt vmcnt(2)
	v_add_u32_e32 v17, v17, v12
	s_waitcnt vmcnt(1)
	v_add_u32_e32 v17, v17, v13
	s_waitcnt vmcnt(0)
	v_add_u32_e32 v17, v17, v14
	v_cmp_eq_u32_e32 vcc, s1, v17
	s_cbranch_vccnz .LBB0_569
	s_and_b32 s26, s3, 0xff
	s_cmp_eq_u32 s26, 0
	s_mov_b64 s[54:55], -1
	s_cbranch_scc1 .LBB0_574
	s_and_b64 vcc, exec, s[54:55]
	s_cbranch_vccz .LBB0_569

.LBB0_588:
	s_and_b32 s1, s0, 0xff
	s_mov_b64 s[22:23], -1
	s_cmp_lg_u32 s1, 0
	s_mov_b64 s[34:35], -1
	s_cbranch_scc0 .LBB0_591
	s_and_b64 vcc, exec, s[34:35]
	s_cbranch_vccz .LBB0_587

.LBB0_605:
	s_and_b32 s1, s0, 0xff
	s_cmp_lg_u32 s1, 0
	s_mov_b64 s[24:25], -1
	s_cbranch_scc0 .LBB0_608
	s_mov_b64 s[34:35], -1
	s_and_b64 vcc, exec, s[24:25]
	s_cbranch_vccz .LBB0_604
